# v37 plus nt cache hint on the final-phase d_out stores
# baseline (speedup 1.0000x reference)
.LBB0_930:
	ds_bpermute_b32 v80, v76, v1
	v_cvt_f32_f16_sdwa v83, v71 dst_sel:DWORD dst_unused:UNUSED_PAD src0_sel:WORD_1
	v_cvt_f32_f16_sdwa v85, v68 dst_sel:DWORD dst_unused:UNUSED_PAD src0_sel:WORD_1
	v_cvt_f32_f16_sdwa v87, v69 dst_sel:DWORD dst_unused:UNUSED_PAD src0_sel:WORD_1
	s_ashr_i32 s5, s4, 31
	s_waitcnt lgkmcnt(0)
	v_add_f32_e32 v80, v1, v80
	ds_bpermute_b32 v81, v77, v80
	v_cvt_f32_f16_sdwa v89, v66 dst_sel:DWORD dst_unused:UNUSED_PAD src0_sel:WORD_1
	v_cvt_f32_f16_sdwa v91, v67 dst_sel:DWORD dst_unused:UNUSED_PAD src0_sel:WORD_1
	s_lshl_b64 s[6:7], s[4:5], 12
	s_add_i32 s2, s15, s33
	s_waitcnt lgkmcnt(0)
	v_add_f32_e32 v82, v80, v81
	ds_bpermute_b32 v84, v78, v82
	v_cvt_f32_f16_sdwa v81, v70 dst_sel:DWORD dst_unused:UNUSED_PAD src0_sel:WORD_1
	v_cvt_f32_f16_e32 v80, v70
	s_add_i32 s4, s4, s12
	s_cmpk_gt_i32 s2, 0xfff
	s_waitcnt lgkmcnt(0)
	v_add_f32_e32 v86, v82, v84
	ds_bpermute_b32 v88, v79, v86
	v_cvt_f32_f16_e32 v82, v71
	v_cvt_f32_f16_e32 v84, v68
	s_cselect_b64 s[10:11], -1, 0
	s_waitcnt lgkmcnt(0)
	v_add_f32_e32 v86, v86, v88
	ds_bpermute_b32 v90, v75, v86
	v_cvt_f32_f16_e32 v86, v69
	v_cvt_f32_f16_e32 v88, v66
	s_waitcnt lgkmcnt(0)
	v_fmamk_f32 v90, v90, 0x3a800000, v0
	v_mul_f32_e32 v92, 0x4b800000, v90
	v_cmp_gt_f32_e32 vcc, s14, v90
	s_nop 1
	v_cndmask_b32_e32 v90, v90, v92, vcc
	v_rsq_f32_e32 v94, v90
	v_cvt_f32_f16_e32 v90, v67
	v_lshl_add_u64 v[92:93], v[64:65], 0, s[6:7]
	v_mul_f32_e32 v95, 0x45800000, v94
	v_cndmask_b32_e32 v94, v94, v95, vcc
	v_pk_mul_f32 v[80:81], v[94:95], v[80:81] op_sel_hi:[0,1]
	v_pk_mul_f32 v[82:83], v[94:95], v[82:83] op_sel_hi:[0,1]
	v_pk_mul_f32 v[84:85], v[94:95], v[84:85] op_sel_hi:[0,1]
	v_pk_mul_f32 v[86:87], v[94:95], v[86:87] op_sel_hi:[0,1]
	v_pk_fma_f32 v[82:83], v[20:21], v[82:83], v[36:37]
	v_pk_fma_f32 v[80:81], v[18:19], v[80:81], v[34:35]
	v_pk_fma_f32 v[86:87], v[24:25], v[86:87], v[40:41]
	v_pk_fma_f32 v[84:85], v[22:23], v[84:85], v[38:39]
	global_store_dwordx4 v[92:93], v[80:83], off nt
	global_store_dwordx4 v[92:93], v[84:87], off offset:1024 nt
	s_nop 0
	v_pk_mul_f32 v[80:81], v[94:95], v[88:89] op_sel_hi:[0,1]
	v_cvt_f32_f16_sdwa v85, v72 dst_sel:DWORD dst_unused:UNUSED_PAD src0_sel:WORD_1
	v_cvt_f32_f16_e32 v84, v72
	v_cvt_f32_f16_sdwa v87, v73 dst_sel:DWORD dst_unused:UNUSED_PAD src0_sel:WORD_1
	v_cvt_f32_f16_e32 v86, v73
	v_pk_mul_f32 v[82:83], v[94:95], v[90:91] op_sel_hi:[0,1]
	v_pk_fma_f32 v[82:83], v[28:29], v[82:83], v[48:49]
	v_pk_fma_f32 v[80:81], v[26:27], v[80:81], v[46:47]
	global_store_dwordx4 v[92:93], v[80:83], off offset:2048 nt
	s_nop 1
	v_pk_mul_f32 v[80:81], v[94:95], v[84:85] op_sel_hi:[0,1]
	v_pk_mul_f32 v[82:83], v[94:95], v[86:87] op_sel_hi:[0,1]
	v_pk_fma_f32 v[82:83], v[32:33], v[82:83], v[44:45]
	v_pk_fma_f32 v[80:81], v[30:31], v[80:81], v[42:43]
	global_store_dwordx4 v[92:93], v[80:83], off offset:3072 nt

; template <bool PRE>
; DI void phase_final(const Params& p, const FinPre& fp) {
;     ...
;   while (u < NTOK / 8) {
;     { const int un = u + G; if (un < NTOK / 8) FIN_LOAD(yb, xb, sb, un); FIN_ROW(ya, xa, sa, u); u = un; }
;     if (u >= NTOK / 8) break;
;     { const int un = u + G; if (un < NTOK / 8) FIN_LOAD(ya, xa, sa, un); FIN_ROW(yb, xb, sb, u); u = un; }
;   }
.LBB0_936:
	s_waitcnt vmcnt(4)
	ds_bpermute_b32 v80, v76, v74
	s_waitcnt vmcnt(3)
	v_cvt_f32_f16_sdwa v83, v51 dst_sel:DWORD dst_unused:UNUSED_PAD src0_sel:WORD_1
	s_waitcnt vmcnt(2)
	v_cvt_f32_f16_sdwa v85, v52 dst_sel:DWORD dst_unused:UNUSED_PAD src0_sel:WORD_1
	v_cvt_f32_f16_sdwa v87, v53 dst_sel:DWORD dst_unused:UNUSED_PAD src0_sel:WORD_1
	s_ashr_i32 s7, s6, 31
	s_waitcnt lgkmcnt(0)
	v_add_f32_e32 v80, v74, v80
	ds_bpermute_b32 v81, v77, v80
	s_waitcnt vmcnt(1)
	v_cvt_f32_f16_sdwa v89, v54 dst_sel:DWORD dst_unused:UNUSED_PAD src0_sel:WORD_1
	v_cvt_f32_f16_sdwa v91, v55 dst_sel:DWORD dst_unused:UNUSED_PAD src0_sel:WORD_1
	s_lshl_b64 s[8:9], s[6:7], 12
	s_cmpk_gt_i32 s15, 0xfff
	s_waitcnt lgkmcnt(0)
	v_add_f32_e32 v82, v80, v81
	ds_bpermute_b32 v84, v78, v82
	v_cvt_f32_f16_sdwa v81, v50 dst_sel:DWORD dst_unused:UNUSED_PAD src0_sel:WORD_1
	v_cvt_f32_f16_e32 v80, v50
	s_mov_b64 s[10:11], -1
	s_waitcnt lgkmcnt(0)
	v_add_f32_e32 v86, v82, v84
	ds_bpermute_b32 v88, v79, v86
	v_cvt_f32_f16_e32 v82, v51
	v_cvt_f32_f16_e32 v84, v52
	s_waitcnt lgkmcnt(0)
	v_add_f32_e32 v86, v86, v88
	ds_bpermute_b32 v90, v75, v86
	v_cvt_f32_f16_e32 v86, v53
	v_cvt_f32_f16_e32 v88, v54
	s_waitcnt lgkmcnt(0)
	v_fmamk_f32 v90, v90, 0x3a800000, v0
	v_mul_f32_e32 v92, 0x4b800000, v90
	v_cmp_gt_f32_e32 vcc, s14, v90
	s_nop 1
	v_cndmask_b32_e32 v90, v90, v92, vcc
	v_rsq_f32_e32 v94, v90
	v_cvt_f32_f16_e32 v90, v55
	v_lshl_add_u64 v[92:93], v[64:65], 0, s[8:9]
	v_mul_f32_e32 v95, 0x45800000, v94
	v_cndmask_b32_e32 v94, v94, v95, vcc
	v_pk_mul_f32 v[80:81], v[94:95], v[80:81] op_sel_hi:[0,1]
	v_pk_mul_f32 v[82:83], v[94:95], v[82:83] op_sel_hi:[0,1]
	v_pk_mul_f32 v[84:85], v[94:95], v[84:85] op_sel_hi:[0,1]
	v_pk_mul_f32 v[86:87], v[94:95], v[86:87] op_sel_hi:[0,1]
	v_pk_fma_f32 v[80:81], v[18:19], v[80:81], v[2:3]
	v_pk_fma_f32 v[82:83], v[20:21], v[82:83], v[4:5]
	v_pk_fma_f32 v[84:85], v[22:23], v[84:85], v[6:7]
	v_pk_fma_f32 v[86:87], v[24:25], v[86:87], v[8:9]
	global_store_dwordx4 v[92:93], v[80:83], off nt
	global_store_dwordx4 v[92:93], v[84:87], off offset:1024 nt
	s_nop 0
	v_pk_mul_f32 v[80:81], v[94:95], v[88:89] op_sel_hi:[0,1]
	s_waitcnt vmcnt(2)
	v_cvt_f32_f16_sdwa v85, v56 dst_sel:DWORD dst_unused:UNUSED_PAD src0_sel:WORD_1
	v_cvt_f32_f16_e32 v84, v56
	v_cvt_f32_f16_sdwa v87, v57 dst_sel:DWORD dst_unused:UNUSED_PAD src0_sel:WORD_1
	v_cvt_f32_f16_e32 v86, v57
	v_pk_mul_f32 v[82:83], v[94:95], v[90:91] op_sel_hi:[0,1]
	v_pk_fma_f32 v[80:81], v[26:27], v[80:81], v[14:15]
	v_pk_fma_f32 v[82:83], v[28:29], v[82:83], v[16:17]
	global_store_dwordx4 v[92:93], v[80:83], off offset:2048 nt
	s_nop 1
	v_pk_mul_f32 v[80:81], v[94:95], v[84:85] op_sel_hi:[0,1]
	v_pk_mul_f32 v[82:83], v[94:95], v[86:87] op_sel_hi:[0,1]
	v_pk_fma_f32 v[80:81], v[30:31], v[80:81], v[10:11]
	v_pk_fma_f32 v[82:83], v[32:33], v[82:83], v[12:13]
	global_store_dwordx4 v[92:93], v[80:83], off offset:3072 nt
	s_cbranch_scc1 .LBB0_931
	s_add_i32 s2, s13, s2
	s_cmpk_lt_i32 s2, 0x1000
	s_mov_b64 s[2:3], -1
	s_cbranch_scc1 .LBB0_939
	s_add_i32 s8, s6, s12
	s_mov_b64 s[2:3], 0
